# kernel prologue: silu(c) staging loop (16 dependent load-wait iterations) replaced by 16 loads issued together and one wait
# baseline (speedup 1.0000x reference)
; __device__ __forceinline__ float silu_f(float x) { return x * __builtin_amdgcn_rcpf(1.0f + fexp(-x)); }
; #define LAUNDER_V(x) asm volatile("" : "+v"(x))
; #define LAUNDER_S(x) asm volatile("" : "+s"(x))
; __device__ __forceinline__ void phase_mod(const float* c, const float* ada_w, const float* ada_b, float* mod, unsigned char* ldsb) {
;     float* cact = (float*)ldsb;
;     float* red = cact + 8192;
;     int tid = threadIdx.x; LAUNDER_V(tid); int bid = blockIdx.x; LAUNDER_S(bid);
;     const int lane = tid & 63, w = __builtin_amdgcn_readfirstlane(tid >> 6);
;     for (int i = tid; i < 8192; i += 512) cact[i] = silu_f(c[i]);
.LBB0_5:
	s_mov_b64 s[12:13], 0x1000
	global_load_dword v204, v[4:5], off
	global_load_dword v205, v[4:5], off offset:2048
	v_lshl_add_u64 v[4:5], v[4:5], 0, s[12:13]
	global_load_dword v206, v[4:5], off
	global_load_dword v207, v[4:5], off offset:2048
	v_lshl_add_u64 v[4:5], v[4:5], 0, s[12:13]
	global_load_dword v208, v[4:5], off
	global_load_dword v209, v[4:5], off offset:2048
	v_lshl_add_u64 v[4:5], v[4:5], 0, s[12:13]
	global_load_dword v210, v[4:5], off
	global_load_dword v211, v[4:5], off offset:2048
	v_lshl_add_u64 v[4:5], v[4:5], 0, s[12:13]
	global_load_dword v212, v[4:5], off
	global_load_dword v213, v[4:5], off offset:2048
	v_lshl_add_u64 v[4:5], v[4:5], 0, s[12:13]
	global_load_dword v214, v[4:5], off
	global_load_dword v215, v[4:5], off offset:2048
	v_lshl_add_u64 v[4:5], v[4:5], 0, s[12:13]
	global_load_dword v216, v[4:5], off
	global_load_dword v217, v[4:5], off offset:2048
	v_lshl_add_u64 v[4:5], v[4:5], 0, s[12:13]
	global_load_dword v218, v[4:5], off
	global_load_dword v219, v[4:5], off offset:2048
	v_lshl_add_u64 v[4:5], v[4:5], 0, s[12:13]
	s_waitcnt vmcnt(0)
	v_mul_f32_e32 v220, 0xbfb8aa3b, v204
	v_mul_f32_e32 v221, 0xbfb8aa3b, v205
	v_mul_f32_e32 v222, 0xbfb8aa3b, v206
	v_mul_f32_e32 v223, 0xbfb8aa3b, v207
	v_exp_f32_e32 v220, v220
	v_exp_f32_e32 v221, v221
	v_exp_f32_e32 v222, v222
	v_exp_f32_e32 v223, v223
	v_add_f32_e32 v220, 1.0, v220
	v_add_f32_e32 v221, 1.0, v221
	v_add_f32_e32 v222, 1.0, v222
	v_add_f32_e32 v223, 1.0, v223
	v_rcp_f32_e32 v220, v220
	v_rcp_f32_e32 v221, v221
	v_rcp_f32_e32 v222, v222
	v_rcp_f32_e32 v223, v223
	v_mul_f32_e32 v204, v204, v220
	v_mul_f32_e32 v205, v205, v221
	v_mul_f32_e32 v206, v206, v222
	v_mul_f32_e32 v207, v207, v223
	ds_write_b32 v6, v204 offset:0
	ds_write_b32 v6, v205 offset:2048
	ds_write_b32 v6, v206 offset:4096
	ds_write_b32 v6, v207 offset:6144
	v_mul_f32_e32 v224, 0xbfb8aa3b, v208
	v_mul_f32_e32 v225, 0xbfb8aa3b, v209
	v_mul_f32_e32 v226, 0xbfb8aa3b, v210
	v_mul_f32_e32 v227, 0xbfb8aa3b, v211
	v_exp_f32_e32 v224, v224
	v_exp_f32_e32 v225, v225
	v_exp_f32_e32 v226, v226
	v_exp_f32_e32 v227, v227
	v_add_f32_e32 v224, 1.0, v224
	v_add_f32_e32 v225, 1.0, v225
	v_add_f32_e32 v226, 1.0, v226
	v_add_f32_e32 v227, 1.0, v227
	v_rcp_f32_e32 v224, v224
	v_rcp_f32_e32 v225, v225
	v_rcp_f32_e32 v226, v226
	v_rcp_f32_e32 v227, v227
	v_mul_f32_e32 v208, v208, v224
	v_mul_f32_e32 v209, v209, v225
	v_mul_f32_e32 v210, v210, v226
	v_mul_f32_e32 v211, v211, v227
	ds_write_b32 v6, v208 offset:8192
	ds_write_b32 v6, v209 offset:10240
	ds_write_b32 v6, v210 offset:12288
	ds_write_b32 v6, v211 offset:14336
	v_mul_f32_e32 v228, 0xbfb8aa3b, v212
	v_mul_f32_e32 v229, 0xbfb8aa3b, v213
	v_mul_f32_e32 v230, 0xbfb8aa3b, v214
	v_mul_f32_e32 v231, 0xbfb8aa3b, v215
	v_exp_f32_e32 v228, v228
	v_exp_f32_e32 v229, v229
	v_exp_f32_e32 v230, v230
	v_exp_f32_e32 v231, v231
	v_add_f32_e32 v228, 1.0, v228
	v_add_f32_e32 v229, 1.0, v229
	v_add_f32_e32 v230, 1.0, v230
	v_add_f32_e32 v231, 1.0, v231
	v_rcp_f32_e32 v228, v228
	v_rcp_f32_e32 v229, v229
	v_rcp_f32_e32 v230, v230
	v_rcp_f32_e32 v231, v231
	v_mul_f32_e32 v212, v212, v228
	v_mul_f32_e32 v213, v213, v229
	v_mul_f32_e32 v214, v214, v230
	v_mul_f32_e32 v215, v215, v231
	ds_write_b32 v6, v212 offset:16384
	ds_write_b32 v6, v213 offset:18432
	ds_write_b32 v6, v214 offset:20480
	ds_write_b32 v6, v215 offset:22528
	v_mul_f32_e32 v232, 0xbfb8aa3b, v216
	v_mul_f32_e32 v233, 0xbfb8aa3b, v217
	v_mul_f32_e32 v234, 0xbfb8aa3b, v218
	v_mul_f32_e32 v235, 0xbfb8aa3b, v219
	v_exp_f32_e32 v232, v232
	v_exp_f32_e32 v233, v233
	v_exp_f32_e32 v234, v234
	v_exp_f32_e32 v235, v235
	v_add_f32_e32 v232, 1.0, v232
	v_add_f32_e32 v233, 1.0, v233
	v_add_f32_e32 v234, 1.0, v234
	v_add_f32_e32 v235, 1.0, v235
	v_rcp_f32_e32 v232, v232
	v_rcp_f32_e32 v233, v233
	v_rcp_f32_e32 v234, v234
	v_rcp_f32_e32 v235, v235
	v_mul_f32_e32 v216, v216, v232
	v_mul_f32_e32 v217, v217, v233
	v_mul_f32_e32 v218, v218, v234
	v_mul_f32_e32 v219, v219, v235
	ds_write_b32 v6, v216 offset:24576
	ds_write_b32 v6, v217 offset:26624
	ds_write_b32 v6, v218 offset:28672
	ds_write_b32 v6, v219 offset:30720
	v_mov_b32_e32 v3, v219
	v_mov_b32_e32 v7, v235
	v_add_u32_e32 v1, 0x2000, v1
	v_add_u32_e32 v6, 0x8000, v6
